# GEMM1 column-tile order permuted pn'=(pn&1)*12+(pn>>1): each round mixes gate and non-gate tiles
# speedup vs baseline: 1.0234x; 1.0021x over previous
; __global__ void __launch_bounds__(512, 2) mega_fwd(Args args) {
;     ...
;     XcdBarrier xbar = xcd_barrier_post((unsigned*)(args.ws), bst);
;     grid.sync();
;     bf16_t* XB = (bf16_t*)(c.ws + WS_XB);
;     for (int ph = args.ph_lo; ph < args.ph_hi; ++ph) {
;         const int l = ph / PH_PER_LAYER, k = ph % PH_PER_LAYER;
;         { int t_ = threadIdx.x; asm volatile("" : "+v"(t_)); c.tid = t_; c.lane = t_ & 63; c.wave = __builtin_amdgcn_readfirstlane(t_ >> 6);
;           int z_ = 0; asm volatile("" : "+s"(z_)); c.zero = z_;
;           int bx = blockIdx.x; asm volatile("" : "+s"(bx)); c.vcu = (c.G % 8 == 0) ? (bx % 8) * (c.G / 8) + bx / 8 : bx; }
.LBB0_15:
	s_or_b64 exec, exec, s[4:5]
	v_readlane_b32 s4, v253, 0
	v_readlane_b32 s5, v253, 1
	s_load_dwordx2 s[4:5], s[4:5], 0xb8
	s_barrier
	s_waitcnt lgkmcnt(0)
	v_writelane_b32 v253, s4, 4
	s_cmp_ge_i32 s4, s5
	s_nop 0
	v_writelane_b32 v253, s5, 5
	s_cbranch_scc1 .LBB0_572
	v_readlane_b32 s16, v253, 0
	v_readlane_b32 s17, v253, 1
	s_load_dwordx4 s[12:15], s[16:17], 0xa8
	s_mov_b32 s84, 0xffff0000
	v_mbcnt_lo_u32_b32 v0, -1, 0
	v_mov_b32_e32 v97, 0
	v_mov_b32_e32 v213, 0x260
	s_waitcnt lgkmcnt(0)
	s_add_u32 s82, s14, 0x1a000000
	s_addc_u32 s83, s15, 0
	s_and_b32 s1, s58, 7
	s_cmp_eq_u32 s1, 0
	s_cselect_b64 s[4:5], -1, 0
	v_writelane_b32 v253, s4, 6
	s_ashr_i32 s1, s58, 3
	v_mov_b32_e32 v214, 0x2000
	v_writelane_b32 v253, s5, 7
	s_add_u32 s4, s14, 0x1400000
	s_addc_u32 s5, s15, 0
	s_add_u32 s33, s14, 0xe000000
	s_addc_u32 s37, s15, 0
	s_add_u32 s89, s14, 0x4000000
	v_writelane_b32 v253, s1, 8
	s_addc_u32 s3, s15, 0
	v_writelane_b32 v253, s4, 9
	s_cmpk_lt_i32 s2, 0x200
	v_mov_b32_e32 v215, 0x3c0881c4
	v_writelane_b32 v253, s5, 10
	s_cselect_b64 s[4:5], -1, 0
	s_ashr_i32 s78, s2, 31
	v_writelane_b32 v253, s4, 11
	s_lshr_b32 s1, s78, 29
	s_ashr_i32 s79, s58, 31
	v_writelane_b32 v253, s5, 12
	s_add_i32 s4, s2, s1
	s_ashr_i32 s1, s4, 3
	s_and_b32 s4, s4, -8
	s_sub_i32 s6, s2, s4
	s_lshl_b32 s7, s6, 6
	s_add_u32 s90, s14, 0x2000000
	s_addc_u32 s91, s15, 0
	s_add_u32 s4, s14, 0x1800000
	s_addc_u32 s5, s15, 0
	v_writelane_b32 v253, s4, 13
	s_cmpk_lt_i32 s2, 0x80
	v_mov_b32_e32 v216, 0xbab64f3b
	v_writelane_b32 v253, s5, 14
	s_cselect_b64 s[4:5], -1, 0
	v_writelane_b32 v253, s4, 15
	s_lshl_b32 s8, s6, 4
	v_mov_b32_e32 v217, 0xda24260
	v_writelane_b32 v253, s5, 16
	s_add_u32 s4, s14, 0x1800080
	s_addc_u32 s5, s15, 0
	v_writelane_b32 v253, s4, 17
	v_mov_b32_e32 v218, 0x3ecc95a3
	v_mov_b32_e32 v219, 0x3727c5ac
	v_writelane_b32 v253, s5, 18
	s_add_u32 s4, s14, 0x3800
	v_writelane_b32 v253, s4, 19
	s_addc_u32 s4, s15, 0
	v_writelane_b32 v253, s4, 20
	s_add_u32 s4, s14, 0x200000
	s_addc_u32 s5, s15, 0
	s_lshl_b32 s26, s58, 3
	s_add_u32 s10, s14, 0xc000000
	s_addc_u32 s11, s15, 0
	v_writelane_b32 v253, s10, 21
	v_mov_b32_e32 v220, 0x23fc0
	v_mov_b32_e32 v221, 0x23fc4
	v_writelane_b32 v253, s11, 22
	s_add_u32 s10, s14, 0x300000
	s_addc_u32 s11, s15, 0
	s_add_u32 s27, s14, 0x6000000
	s_addc_u32 s28, s15, 0
	s_add_u32 s29, s14, 0x8000000
	v_writelane_b32 v253, s10, 23
	s_addc_u32 s30, s15, 0
	v_mov_b32_e32 v222, 1
	v_writelane_b32 v253, s11, 24
	s_add_u32 s10, s14, 0xa000000
	s_addc_u32 s11, s15, 0
	s_add_u32 s9, s14, 0x100000
	v_writelane_b32 v253, s9, 25
	s_addc_u32 s9, s15, 0
	s_add_u32 s12, s14, 0x800000
	v_writelane_b32 v253, s9, 26
	s_addc_u32 s13, s15, 0
	v_writelane_b32 v253, s12, 27
	s_cmpk_lt_i32 s2, 0xc00
	v_mov_b64_e32 v[194:195], 0x200
	v_writelane_b32 v253, s13, 28
	s_cselect_b64 s[12:13], -1, 0
	v_writelane_b32 v253, s12, 29
	v_mov_b64_e32 v[196:197], 0x1ff
	v_mov_b32_e32 v223, 0x7f800000
	v_writelane_b32 v253, s13, 30
	s_add_u32 s12, s14, 0x1600000
	s_addc_u32 s13, s15, 0
	v_writelane_b32 v253, s12, 31
	v_not_b32_e32 v224, 63
	v_not_b32_e32 v225, 31
	v_writelane_b32 v253, s13, 32
	s_add_u32 s12, s14, 0x1400600
	s_addc_u32 s13, s15, 0
	v_writelane_b32 v253, s12, 33
	v_mov_b32_e32 v226, 0x7fc00000
	v_mov_b32_e32 v227, 0xff800000
	v_writelane_b32 v253, s13, 34
	s_add_u32 s12, s14, 0x1400200
	s_addc_u32 s13, s15, 0
	v_writelane_b32 v253, s12, 35
	s_add_u32 s9, s14, 0x400000
	v_mbcnt_hi_u32_b32 v228, -1, v0
	v_writelane_b32 v253, s13, 36
	v_writelane_b32 v253, s9, 37
	s_addc_u32 s9, s15, 0
	s_add_u32 s12, s14, 0x200
	v_writelane_b32 v253, s9, 38
	s_addc_u32 s13, s15, 0
	v_writelane_b32 v253, s12, 39
	v_mov_b64_e32 v[198:199], 0xbff
	s_mov_b32 s87, 0xf800000
	v_writelane_b32 v253, s13, 40
	s_add_u32 s12, s14, 0x1000
	s_addc_u32 s13, s15, 0
	v_writelane_b32 v253, s12, 41
	s_mov_b32 s93, 0xc3160000
	s_mov_b32 s95, 0x41c00000
	v_writelane_b32 v253, s13, 42
	s_add_u32 s12, s14, 0x1100
	s_addc_u32 s13, s15, 0
	v_writelane_b32 v253, s12, 43
	s_mov_b32 s35, 0
	s_mov_b64 s[96:97], 0x4000
	v_writelane_b32 v253, s13, 44
	s_add_u32 s12, s14, 0x1200
	s_addc_u32 s13, s15, 0
	v_writelane_b32 v253, s12, 45
	s_mov_b64 s[18:19], 0x10000
	s_mov_b64 s[56:57], 0x20000
	v_writelane_b32 v253, s13, 46
	s_add_u32 s12, s14, 0x1300
	s_addc_u32 s13, s15, 0
	v_writelane_b32 v253, s12, 47
	s_cmp_eq_u32 s0, 15
	s_mov_b32 s85, -1
	v_writelane_b32 v253, s13, 48
	s_cselect_b64 s[12:13], -1, 0
	v_writelane_b32 v253, s12, 49
	s_cmp_eq_u32 s0, 14
	s_mov_b32 s88, 0x3fd744fd
	v_writelane_b32 v253, s13, 50
	s_cselect_b64 s[12:13], -1, 0
	v_writelane_b32 v253, s12, 51
	s_cmp_eq_u32 s0, 13
	s_nop 0
	v_writelane_b32 v253, s13, 52
;     __host__ __device__ bool next(int i, Unit& u) const {
;         const long L = (long)i * G + c; if (L >= nwg) return false;
;         int wgid = (int)L; { const int q = nwg / NXCD, r = nwg % NXCD, xcd = wgid % NXCD, off = wgid / NXCD; wgid = (xcd < r ? xcd * (q + 1) : r * (q + 1) + (xcd - r) * q) + off; }
;         const int nig = WGM * nN, gid = wgid / nig, fm = gid * WGM, gsz = (nM - fm) < WGM ? (nM - fm) : WGM;
;         u.pm = fm + ((wgid % nig) % gsz); u.pn = (wgid % nig) / gsz; return true;
;     __device__ __forceinline__ void acc_init(f32x4 (&ini)[2][2], const Unit& u) const {
;         int t__ = threadIdx.x; asm volatile("" : "+v"(t__)); const int wid__ = __builtin_amdgcn_readfirstlane(t__ >> 6), wc = wid__ & 3, fq = (t__ & 63) >> 4;
;         const int pn = u.pn; const float* bp = bias + pn * BM + (pn >= 8 ? 8 : 0) + wc * 32 + 8 * fq;
	s_cselect_b64 s[12:13], -1, 0
	v_writelane_b32 v253, s12, 53
	s_cmp_eq_u32 s0, 12
	s_nop 0
	v_writelane_b32 v253, s13, 54
	s_cselect_b64 s[12:13], -1, 0
	v_writelane_b32 v253, s12, 55
	s_cmp_eq_u32 s0, 11
	s_nop 0
	v_writelane_b32 v253, s13, 56
	s_cselect_b64 s[12:13], -1, 0
	v_writelane_b32 v253, s12, 57
	s_cmp_eq_u32 s0, 10
	s_nop 0
	v_writelane_b32 v253, s13, 58
	s_cselect_b64 s[12:13], -1, 0
	v_writelane_b32 v253, s12, 59
	s_cmp_eq_u32 s0, 9
	s_nop 0
	v_writelane_b32 v253, s13, 60
	s_cselect_b64 s[12:13], -1, 0
	v_writelane_b32 v253, s12, 61
	s_cmp_eq_u32 s0, 8
	s_nop 0
	v_writelane_b32 v253, s13, 62
	s_cselect_b64 s[12:13], -1, 0
	v_writelane_b32 v253, s12, 63
	s_cmp_eq_u32 s0, 7
	s_nop 0
	v_writelane_b32 v252, s13, 0
	s_cselect_b64 s[12:13], -1, 0
	v_writelane_b32 v252, s12, 1
	s_cmp_eq_u32 s0, 6
	s_nop 0
	v_writelane_b32 v252, s13, 2
	s_cselect_b64 s[12:13], -1, 0
	v_writelane_b32 v252, s12, 3
	s_cmp_eq_u32 s0, 5
	s_nop 0
	v_writelane_b32 v252, s13, 4
	s_cselect_b64 s[12:13], -1, 0
	v_writelane_b32 v252, s12, 5
	s_cmp_eq_u32 s0, 4
	s_nop 0
	v_writelane_b32 v252, s13, 6
	s_cselect_b64 s[12:13], -1, 0
	v_writelane_b32 v252, s12, 7
	s_cmp_eq_u32 s0, 3
	s_nop 0
	v_writelane_b32 v252, s13, 8
	s_cselect_b64 s[12:13], -1, 0
	v_writelane_b32 v252, s12, 9
	s_cmp_eq_u32 s0, 2
	s_nop 0
	v_writelane_b32 v252, s13, 10
	s_cselect_b64 s[12:13], -1, 0
	v_writelane_b32 v252, s12, 11
	s_cmp_eq_u32 s0, 1
	s_nop 0
	v_writelane_b32 v252, s13, 12
	s_cselect_b64 s[12:13], -1, 0
	v_writelane_b32 v252, s12, 13
	s_cmp_eq_u32 s0, 0
	s_nop 0
	v_writelane_b32 v252, s13, 14
	s_cselect_b64 s[12:13], -1, 0
	s_lshl_b32 s0, s0, 8
	s_add_u32 s0, s14, s0
	v_writelane_b32 v252, s12, 15
	s_addc_u32 s9, s15, 0
	s_nop 0
	v_writelane_b32 v252, s13, 16
	s_add_u32 s12, s0, 0x1400
	s_addc_u32 s13, s9, 0
	v_writelane_b32 v252, s12, 17
	s_nop 1
	v_writelane_b32 v252, s13, 18
	s_add_u32 s12, s0, 0x2400
	s_addc_u32 s13, s9, 0
	v_writelane_b32 v252, s12, 19
	s_mul_i32 s0, s6, 0x41
	s_nop 0
	v_writelane_b32 v252, s13, 20
	s_add_u32 s12, s14, 0x3400
	s_addc_u32 s13, s15, 0
	v_writelane_b32 v252, s12, 21
	s_nop 1
	v_writelane_b32 v252, s13, 22
	s_add_u32 s12, s14, 0x3500
	s_addc_u32 s13, s15, 0
	s_cmp_lt_i32 s6, 0
	s_cselect_b32 s0, s0, s7
	s_mul_i32 s7, s6, 17
	s_cselect_b32 s7, s7, s8
	s_movk_i32 s8, 0x181
	s_cselect_b32 s8, s8, 0x180
	s_add_i32 s0, s0, s1
	s_ashr_i32 s9, s0, 31
	s_lshr_b32 s9, s9, 28
	v_writelane_b32 v252, s12, 23
	s_add_i32 s9, s0, s9
	s_nop 0
	v_writelane_b32 v252, s13, 24
	s_and_b32 s12, s9, 0xfff0
	s_sub_i32 s0, s0, s12
	s_bfe_i32 s12, s0, 0x80000
	s_bfe_u32 s12, s12, 0x2000d
	s_add_i32 s12, s0, s12
	s_and_b32 s13, s12, 0xfc
	s_sub_i32 s0, s0, s13
	s_ashr_i32 s9, s9, 4
	s_lshl_b32 s9, s9, 2
	s_sext_i32_i8 s0, s0
	s_add_i32 s9, s9, s0
	s_mul_i32 s0, s6, s8
	s_add_i32 s0, s0, s1
	s_add_i32 s8, s7, s1
	s_mul_hi_i32 s1, s0, 0x2aaaaaab
	s_lshr_b32 s6, s1, 31
	s_ashr_i32 s1, s1, 4
	s_add_i32 s1, s1, s6
	s_mul_i32 s6, s1, 0x60
	s_sub_i32 s0, s0, s6
	s_bfe_i32 s6, s0, 0x80000
	s_bfe_u32 s6, s6, 0x2000d
	s_add_i32 s6, s0, s6
	s_and_b32 s7, s6, 0xfc
	s_sub_i32 s0, s0, s7
	s_lshl_b32 s1, s1, 2
	s_sext_i32_i8 s0, s0
	s_add_i32 s13, s1, s0
	s_load_dword s0, s[16:17], 0xc8
	s_waitcnt lgkmcnt(0)
	s_mul_i32 s0, s59, s0
	s_mul_i32 s0, s0, s58
	v_writelane_b32 v252, s0, 25
	s_bfe_i32 s0, s12, 0x80000
	s_sext_i32_i16 s0, s0
	s_ashr_i32 s1, s0, 2
	s_lshr_b32 s0, s0, 2
	v_writelane_b32 v252, s1, 26
	s_bfe_i64 s[0:1], s[0:1], 0x100000
	v_writelane_b32 v252, s0, 27
	s_mov_b32 s59, 0xffff0000
	s_nop 0
	v_writelane_b32 v252, s1, 28
	s_bfe_i32 s0, s6, 0x80000
	s_sext_i32_i16 s0, s0
	s_lshr_b32 s0, s0, 2
	s_and_b32 s98, s0, 1
	s_lshr_b32 s0, s0, 1
	s_mul_i32 s98, s98, 12
	s_add_i32 s0, s0, s98
	s_sext_i32_i16 s1, s0
	v_writelane_b32 v252, s9, 29
	s_ashr_i32 s9, s9, 31
	s_lshl_b32 s6, s1, 8
	v_writelane_b32 v252, s9, 30
	s_ashr_i32 s7, s6, 31
	v_writelane_b32 v252, s8, 31
	s_ashr_i32 s8, s8, 31
	v_writelane_b32 v252, s8, 32
	s_cmp_lt_i32 s1, 8
	v_writelane_b32 v252, s1, 33
	s_cselect_b32 s1, 0, 8
	s_bfe_i64 s[8:9], s[0:1], 0x100000
	v_writelane_b32 v252, s8, 34
	s_ashr_i32 s0, s13, 31
	s_nop 0
	v_writelane_b32 v252, s9, 35
	v_writelane_b32 v252, s13, 36
	s_add_u32 s8, s14, 0xc008000
	v_writelane_b32 v252, s0, 37
	s_addc_u32 s9, s15, 0
	v_writelane_b32 v252, s8, 38
	s_lshl_b64 s[6:7], s[6:7], 2
	s_lshl_b32 s0, s1, 2
	v_writelane_b32 v252, s9, 39
	v_writelane_b32 v252, s6, 40
	s_mov_b32 s1, 0x2002000
	s_mov_b64 s[8:9], 0x80
	v_writelane_b32 v252, s7, 41
	v_writelane_b32 v252, s0, 42
	s_lshl_b32 s0, s58, 7
	v_writelane_b32 v252, s0, 43
	s_brev_b32 s7, 64
	s_mov_b64 s[14:15], 0x30000
	v_writelane_b32 v252, s78, 44
	v_writelane_b32 v252, s79, 45
	s_branch .LBB0_20

;     __host__ __device__ bool next(int i, Unit& u) const {
;         const long L = (long)i * G + c; if (L >= nwg) return false;
;         int wgid = (int)L; { const int q = nwg / NXCD, r = nwg % NXCD, xcd = wgid % NXCD, off = wgid / NXCD; wgid = (xcd < r ? xcd * (q + 1) : r * (q + 1) + (xcd - r) * q) + off; }
;         const int nig = WGM * nN, gid = wgid / nig, fm = gid * WGM, gsz = (nM - fm) < WGM ? (nM - fm) : WGM;
;         u.pm = fm + ((wgid % nig) % gsz); u.pn = (wgid % nig) / gsz; return true;
; template <class Epi, class Sched, bool ALIGN_EPI = false, bool SP2 = false>
; __device__ __forceinline__ void gemm_phase(PG8_LAS unsigned char* lds, const Gemm g, const Sched& S, const Epi& E) {
;     ...
;         const bool has_next = S.next(ui + 1, nxt);
;         const char* nA = has_next ? (const char*)g.A + (size_t)nxt.pm * tstep : cA; const char* nB = has_next ? (const char*)g.Bt + (size_t)nxt.pn * tstep : cB;
.LBB0_393:
	s_add_i32 s69, s69, 1
	s_mul_i32 s38, s69, s79
	s_mul_hi_u32 s39, s69, s58
	s_add_i32 s39, s39, s38
	s_mul_i32 s38, s69, s58
	s_add_u32 s38, s38, s2
	s_addc_u32 s39, s39, s78
	v_mov_b64_e32 v[16:17], 0xc00
	v_cmp_gt_i64_e32 vcc, s[38:39], v[198:199]
	v_cmp_lt_i64_e64 s[40:41], s[38:39], v[16:17]
	s_cbranch_vccnz .LBB0_395
	s_ashr_i32 s39, s38, 31
	s_lshr_b32 s39, s39, 29
	s_add_i32 s39, s38, s39
	s_ashr_i32 s52, s39, 3
	s_and_b32 s39, s39, -8
	s_sub_i32 s38, s38, s39
	s_cmp_lt_i32 s38, 0
	s_movk_i32 s24, 0x181
	s_cselect_b32 s39, s24, 0x180
	s_mul_i32 s38, s38, s39
	s_add_i32 s38, s38, s52
	s_mul_hi_i32 s39, s38, 0x2aaaaaab
	s_lshr_b32 s52, s39, 31
	s_ashr_i32 s39, s39, 4
	s_add_i32 s39, s39, s52
	s_lshl_b32 s52, s39, 2
	s_sub_i32 s53, 0x80, s52
	s_min_i32 s53, s53, 4
	s_abs_i32 s55, s53
	v_cvt_f32_u32_e32 v16, s55
	s_sub_i32 s71, 0, s55
	s_mulk_i32 s39, 0x60
	s_sub_i32 s38, s38, s39
	v_rcp_iflag_f32_e32 v16, v16
	s_abs_i32 s39, s38
	s_xor_b32 s70, s38, s53
	s_ashr_i32 s70, s70, 31
	v_mul_f32_e32 v16, 0x4f7ffffe, v16
	v_cvt_u32_f32_e32 v16, v16
	s_nop 0
	v_readfirstlane_b32 s73, v16
	s_mul_i32 s71, s71, s73
	s_mul_hi_u32 s71, s73, s71
	s_add_i32 s73, s73, s71
	s_mul_hi_u32 s71, s39, s73
	s_mul_i32 s73, s71, s55
	s_sub_i32 s39, s39, s73
	s_add_i32 s74, s71, 1
	s_sub_i32 s73, s39, s55
	s_cmp_ge_u32 s39, s55
	s_cselect_b32 s71, s74, s71
	s_cselect_b32 s39, s73, s39
	s_add_i32 s73, s71, 1
	s_cmp_ge_u32 s39, s55
	s_cselect_b32 s39, s73, s71
	s_xor_b32 s39, s39, s70
	s_sub_i32 s70, s39, s70
	s_mul_i32 s39, s70, s53
	s_sub_i32 s38, s38, s39
	s_add_i32 s71, s52, s38
	s_and_b32 s98, s70, 1
	s_lshr_b32 s70, s70, 1
	s_mul_i32 s98, s98, 12
	s_add_i32 s70, s70, s98
